# P2 slices: second w_cq row requested together with the first
# speedup vs baseline: 1.0057x; 1.0004x over previous
.LBB0_216:
	s_waitcnt vmcnt(0)
	v_mov_b64_e32 v[6:7], s[92:93]
	flat_load_dwordx2 v[2:3], v[6:7] offset:64 sc0 sc1
	s_waitcnt vmcnt(0)
	s_lshl_b32 s0, s25, 4
	s_lshl_b32 s1, s24, 1
	s_add_i32 s0, s0, s1
	s_ashr_i32 s1, s0, 31
	s_lshl_b64 s[4:5], s[0:1], 2
	s_lshl_b64 s[6:7], s[0:1], 14
	v_lshlrev_b64 v[8:9], 4, v[134:135]
	v_lshl_add_u64 v[12:13], v[134:135], 3, s[14:15]
	s_lshl_b32 s10, s24, 12
	s_and_b32 s10, s10, 0x1000
	s_waitcnt lgkmcnt(0)
	v_lshl_add_u64 v[2:3], v[2:3], 0, s[4:5]
	flat_load_dword v18, v[2:3]
	global_load_dword v128, v[2:3], off offset:4
	s_nop 0
	flat_load_dwordx2 v[2:3], v[6:7] offset:80 sc0 sc1
	s_waitcnt vmcnt(0) lgkmcnt(0)
	v_lshl_add_u64 v[2:3], v[2:3], 0, s[6:7]
	v_lshl_add_u64 v[10:11], v[2:3], 0, v[8:9]
	v_add_co_u32_e32 v212, vcc, 0x1000, v10
	s_nop 1
	v_addc_co_u32_e32 v213, vcc, 0, v11, vcc
	v_add_co_u32_e32 v228, vcc, 0x2000, v10
	s_nop 1
	v_addc_co_u32_e32 v229, vcc, 0, v11, vcc
	v_add_co_u32_e32 v244, vcc, 0x3000, v10
	s_nop 1
	v_addc_co_u32_e32 v245, vcc, 0, v11, vcc
	global_load_dwordx4 v[184:187], v[10:11], off nt
	global_load_dwordx4 v[188:191], v[10:11], off offset:1024 nt
	global_load_dwordx4 v[192:195], v[10:11], off offset:2048 nt
	global_load_dwordx4 v[196:199], v[10:11], off offset:3072 nt
	global_load_dwordx4 v[200:203], v[212:213], off nt
	global_load_dwordx4 v[204:207], v[212:213], off offset:1024 nt
	global_load_dwordx4 v[208:211], v[212:213], off offset:2048 nt
	global_load_dwordx4 v[212:215], v[212:213], off offset:3072 nt
	global_load_dwordx4 v[216:219], v[228:229], off nt
	global_load_dwordx4 v[220:223], v[228:229], off offset:1024 nt
	global_load_dwordx4 v[224:227], v[228:229], off offset:2048 nt
	global_load_dwordx4 v[228:231], v[228:229], off offset:3072 nt
	global_load_dwordx4 v[232:235], v[244:245], off nt
	global_load_dwordx4 v[236:239], v[244:245], off offset:1024 nt
	global_load_dwordx4 v[240:243], v[244:245], off offset:2048 nt
	global_load_dwordx4 v[244:247], v[244:245], off offset:3072 nt
	v_add_co_u32_e32 v76, vcc, 0x4000, v10
	s_nop 1
	v_addc_co_u32_e32 v77, vcc, 0, v11, vcc
	v_add_co_u32_e32 v92, vcc, 0x5000, v10
	s_nop 1
	v_addc_co_u32_e32 v93, vcc, 0, v11, vcc
	v_add_co_u32_e32 v108, vcc, 0x6000, v10
	s_nop 1
	v_addc_co_u32_e32 v109, vcc, 0, v11, vcc
	v_add_co_u32_e32 v124, vcc, 0x7000, v10
	s_nop 1
	v_addc_co_u32_e32 v125, vcc, 0, v11, vcc
	global_load_dwordx4 v[64:67], v[76:77], off nt
	global_load_dwordx4 v[68:71], v[76:77], off offset:1024 nt
	global_load_dwordx4 v[72:75], v[76:77], off offset:2048 nt
	global_load_dwordx4 v[76:79], v[76:77], off offset:3072 nt
	global_load_dwordx4 v[80:83], v[92:93], off nt
	global_load_dwordx4 v[84:87], v[92:93], off offset:1024 nt
	global_load_dwordx4 v[88:91], v[92:93], off offset:2048 nt
	global_load_dwordx4 v[92:95], v[92:93], off offset:3072 nt
	global_load_dwordx4 v[96:99], v[108:109], off nt
	global_load_dwordx4 v[100:103], v[108:109], off offset:1024 nt
	global_load_dwordx4 v[104:107], v[108:109], off offset:2048 nt
	global_load_dwordx4 v[108:111], v[108:109], off offset:3072 nt
	global_load_dwordx4 v[112:115], v[124:125], off nt
	global_load_dwordx4 v[116:119], v[124:125], off offset:1024 nt
	global_load_dwordx4 v[120:123], v[124:125], off offset:2048 nt
	global_load_dwordx4 v[124:127], v[124:125], off offset:3072 nt
	s_lshl_b64 s[6:7], s[0:1], 13
	v_lshl_add_u64 v[14:15], v[12:13], 0, s[6:7]
	s_movk_i32 s1, 0x1000
	v_add_co_u32_e32 v16, vcc, s1, v10
	s_movk_i32 s6, 0x2000
	s_nop 0
	v_addc_co_u32_e32 v17, vcc, 0, v11, vcc
	s_movk_i32 s7, 0x3000
	s_waitcnt vmcnt(0) lgkmcnt(0)
	v_mov_b32_e32 v2, v184
	v_mov_b32_e32 v3, v185
	v_mov_b32_e32 v4, v186
	v_mov_b32_e32 v5, v187
	v_mul_f32_e32 v2, v18, v2
	v_mul_f32_e32 v3, v18, v3
	v_mul_f32_e32 v4, v18, v4
	v_mul_f32_e32 v5, v18, v5
	v_cvt_pk_bf16_f32 v2, v2, v3
	v_cvt_pk_bf16_f32 v3, v4, v5
	global_store_dwordx2 v[14:15], v[2:3], off
	s_nop 1
	v_mov_b32_e32 v2, v188
	v_mov_b32_e32 v3, v189
	v_mov_b32_e32 v4, v190
	v_mov_b32_e32 v5, v191
	v_mul_f32_e32 v2, v18, v2
	v_mul_f32_e32 v3, v18, v3
	v_mul_f32_e32 v4, v18, v4
	v_mul_f32_e32 v5, v18, v5
	v_cvt_pk_bf16_f32 v2, v2, v3
	v_cvt_pk_bf16_f32 v3, v4, v5
	global_store_dwordx2 v[14:15], v[2:3], off offset:512
	s_nop 1
	v_mov_b32_e32 v2, v192
	v_mov_b32_e32 v3, v193
	v_mov_b32_e32 v4, v194
	v_mov_b32_e32 v5, v195
	v_mul_f32_e32 v2, v18, v2
	v_mul_f32_e32 v3, v18, v3
	v_mul_f32_e32 v4, v18, v4
	v_mul_f32_e32 v5, v18, v5
	v_cvt_pk_bf16_f32 v2, v2, v3
	v_cvt_pk_bf16_f32 v3, v4, v5
	global_store_dwordx2 v[14:15], v[2:3], off offset:1024
	s_nop 1
	v_mov_b32_e32 v2, v196
	v_mov_b32_e32 v3, v197
	v_mov_b32_e32 v4, v198
	v_mov_b32_e32 v5, v199
	v_mul_f32_e32 v2, v18, v2
	v_mul_f32_e32 v3, v18, v3
	v_mul_f32_e32 v4, v18, v4
	v_mul_f32_e32 v5, v18, v5
	v_cvt_pk_bf16_f32 v2, v2, v3
	v_cvt_pk_bf16_f32 v3, v4, v5
	global_store_dwordx2 v[14:15], v[2:3], off offset:1536
	s_nop 1
	v_mov_b32_e32 v2, v200
	v_mov_b32_e32 v3, v201
	v_mov_b32_e32 v4, v202
	v_mov_b32_e32 v5, v203
	v_mul_f32_e32 v2, v18, v2
	v_mul_f32_e32 v3, v18, v3
	v_mul_f32_e32 v4, v18, v4
	v_mul_f32_e32 v5, v18, v5
	v_cvt_pk_bf16_f32 v2, v2, v3
	v_cvt_pk_bf16_f32 v3, v4, v5
	global_store_dwordx2 v[14:15], v[2:3], off offset:2048
	s_nop 1
	v_mov_b32_e32 v2, v204
	v_mov_b32_e32 v3, v205
	v_mov_b32_e32 v4, v206
	v_mov_b32_e32 v5, v207
	v_mul_f32_e32 v2, v18, v2
	v_mul_f32_e32 v3, v18, v3
	v_mul_f32_e32 v4, v18, v4
	v_mul_f32_e32 v5, v18, v5
	v_cvt_pk_bf16_f32 v2, v2, v3
	v_cvt_pk_bf16_f32 v3, v4, v5
	global_store_dwordx2 v[14:15], v[2:3], off offset:2560
	s_nop 1
	v_mov_b32_e32 v2, v208
	v_mov_b32_e32 v3, v209
	v_mov_b32_e32 v4, v210
	v_mov_b32_e32 v5, v211
	v_mul_f32_e32 v2, v18, v2
	v_mul_f32_e32 v3, v18, v3
	v_mul_f32_e32 v4, v18, v4
	v_mul_f32_e32 v5, v18, v5
	v_cvt_pk_bf16_f32 v2, v2, v3
	v_cvt_pk_bf16_f32 v3, v4, v5
	global_store_dwordx2 v[14:15], v[2:3], off offset:3072
	s_nop 1
	v_mov_b32_e32 v2, v212
	v_mov_b32_e32 v3, v213
	v_mov_b32_e32 v4, v214
	v_mov_b32_e32 v5, v215
	v_add_co_u32_e32 v16, vcc, s6, v10
	v_mul_f32_e32 v2, v18, v2
	v_mul_f32_e32 v3, v18, v3
	v_addc_co_u32_e32 v17, vcc, 0, v11, vcc
	v_mul_f32_e32 v4, v18, v4
	v_mul_f32_e32 v5, v18, v5
	v_cvt_pk_bf16_f32 v2, v2, v3
	v_cvt_pk_bf16_f32 v3, v4, v5
	global_store_dwordx2 v[14:15], v[2:3], off offset:3584
	s_nop 1
	v_mov_b32_e32 v2, v216
	v_mov_b32_e32 v3, v217
	v_mov_b32_e32 v4, v218
	v_mov_b32_e32 v5, v219
	v_add_co_u32_e32 v14, vcc, s1, v14
	v_mul_f32_e32 v2, v18, v2
	v_addc_co_u32_e32 v15, vcc, 0, v15, vcc
	v_mul_f32_e32 v3, v18, v3
	v_mul_f32_e32 v4, v18, v4
	v_mul_f32_e32 v5, v18, v5
	v_cvt_pk_bf16_f32 v2, v2, v3
	v_cvt_pk_bf16_f32 v3, v4, v5
	global_store_dwordx2 v[14:15], v[2:3], off
	s_nop 1
	v_mov_b32_e32 v2, v220
	v_mov_b32_e32 v3, v221
	v_mov_b32_e32 v4, v222
	v_mov_b32_e32 v5, v223
	v_add_co_u32_e32 v10, vcc, s7, v10
	v_mul_f32_e32 v2, v18, v2
	v_mul_f32_e32 v3, v18, v3
	v_mul_f32_e32 v4, v18, v4
	v_mul_f32_e32 v5, v18, v5
	v_cvt_pk_bf16_f32 v2, v2, v3
	v_cvt_pk_bf16_f32 v3, v4, v5
	global_store_dwordx2 v[14:15], v[2:3], off offset:512
	s_nop 1
	v_mov_b32_e32 v2, v224
	v_mov_b32_e32 v3, v225
	v_mov_b32_e32 v4, v226
	v_mov_b32_e32 v5, v227
	v_addc_co_u32_e32 v11, vcc, 0, v11, vcc
	v_mul_f32_e32 v2, v18, v2
	v_mul_f32_e32 v3, v18, v3
	v_mul_f32_e32 v4, v18, v4
	v_mul_f32_e32 v5, v18, v5
	v_cvt_pk_bf16_f32 v2, v2, v3
	v_cvt_pk_bf16_f32 v3, v4, v5
	global_store_dwordx2 v[14:15], v[2:3], off offset:1024
	s_nop 1
	v_mov_b32_e32 v2, v228
	v_mov_b32_e32 v3, v229
	v_mov_b32_e32 v4, v230
	v_mov_b32_e32 v5, v231
	v_mul_f32_e32 v2, v18, v2
	v_mul_f32_e32 v3, v18, v3
	v_mul_f32_e32 v4, v18, v4
	v_mul_f32_e32 v5, v18, v5
	v_cvt_pk_bf16_f32 v2, v2, v3
	v_cvt_pk_bf16_f32 v3, v4, v5
	global_store_dwordx2 v[14:15], v[2:3], off offset:1536
	s_nop 1
	v_mov_b32_e32 v2, v232
	v_mov_b32_e32 v3, v233
	v_mov_b32_e32 v4, v234
	v_mov_b32_e32 v5, v235
	v_mul_f32_e32 v2, v18, v2
	v_mul_f32_e32 v3, v18, v3
	v_mul_f32_e32 v4, v18, v4
	v_mul_f32_e32 v5, v18, v5
	v_cvt_pk_bf16_f32 v2, v2, v3
	v_cvt_pk_bf16_f32 v3, v4, v5
	global_store_dwordx2 v[14:15], v[2:3], off offset:2048
	s_nop 1
	v_mov_b32_e32 v2, v236
	v_mov_b32_e32 v3, v237
	v_mov_b32_e32 v4, v238
	v_mov_b32_e32 v5, v239
	v_mul_f32_e32 v2, v18, v2
	v_mul_f32_e32 v3, v18, v3
	v_mul_f32_e32 v4, v18, v4
	v_mul_f32_e32 v5, v18, v5
	v_cvt_pk_bf16_f32 v2, v2, v3
	v_cvt_pk_bf16_f32 v3, v4, v5
	global_store_dwordx2 v[14:15], v[2:3], off offset:2560
	s_nop 1
	v_mov_b32_e32 v2, v240
	v_mov_b32_e32 v3, v241
	v_mov_b32_e32 v4, v242
	v_mov_b32_e32 v5, v243
	v_mul_f32_e32 v2, v18, v2
	v_mul_f32_e32 v3, v18, v3
	v_mul_f32_e32 v4, v18, v4
	v_mul_f32_e32 v5, v18, v5
	v_cvt_pk_bf16_f32 v2, v2, v3
	v_cvt_pk_bf16_f32 v3, v4, v5
	global_store_dwordx2 v[14:15], v[2:3], off offset:3072
	s_nop 1
	v_mov_b32_e32 v2, v244
	v_mov_b32_e32 v3, v245
	v_mov_b32_e32 v4, v246
	v_mov_b32_e32 v5, v247
	v_mul_f32_e32 v2, v18, v2
	v_mul_f32_e32 v3, v18, v3
	v_mul_f32_e32 v4, v18, v4
	v_mul_f32_e32 v5, v18, v5
	v_cvt_pk_bf16_f32 v2, v2, v3
	v_cvt_pk_bf16_f32 v3, v4, v5
	global_store_dwordx2 v[14:15], v[2:3], off offset:3584
	v_lshl_add_u64 v[2:3], v[2:3], 0, s[4:5]
	s_nop 0
	s_or_b32 s4, s0, 1
	s_ashr_i32 s5, s4, 31
	s_lshl_b64 s[8:9], s[4:5], 14
	s_lshl_b64 s[4:5], s[4:5], 13
	s_waitcnt lgkmcnt(0)
	v_lshl_add_u64 v[2:3], v[2:3], 0, s[8:9]
	v_lshl_add_u64 v[6:7], v[2:3], 0, v[8:9]
	v_lshl_add_u64 v[8:9], v[12:13], 0, s[4:5]
	v_add_co_u32_e32 v10, vcc, s1, v6
	s_add_i32 s4, s24, s57
	s_nop 0
	v_addc_co_u32_e32 v11, vcc, 0, v7, vcc
	s_lshl_b32 s4, s4, 3
	s_mov_b64 s[8:9], 0x26000100
	s_movk_i32 s5, 0xffe0
	s_waitcnt vmcnt(16) lgkmcnt(0)
	v_mov_b32_e32 v20, v128
	v_mov_b32_e32 v2, v64
	v_mov_b32_e32 v3, v65
	v_mov_b32_e32 v4, v66
	v_mov_b32_e32 v5, v67
	v_mul_f32_e32 v2, v20, v2
	v_mul_f32_e32 v3, v20, v3
	v_mul_f32_e32 v4, v20, v4
	v_mul_f32_e32 v5, v20, v5
	v_cvt_pk_bf16_f32 v2, v2, v3
	v_cvt_pk_bf16_f32 v3, v4, v5
	global_store_dwordx2 v[8:9], v[2:3], off
	s_nop 1
	v_mov_b32_e32 v2, v68
	v_mov_b32_e32 v3, v69
	v_mov_b32_e32 v4, v70
	v_mov_b32_e32 v5, v71
	v_mul_f32_e32 v2, v20, v2
	v_mul_f32_e32 v3, v20, v3
	v_mul_f32_e32 v4, v20, v4
	v_mul_f32_e32 v5, v20, v5
	v_cvt_pk_bf16_f32 v2, v2, v3
	v_cvt_pk_bf16_f32 v3, v4, v5
	global_store_dwordx2 v[8:9], v[2:3], off offset:512
	s_nop 1
	v_mov_b32_e32 v2, v72
	v_mov_b32_e32 v3, v73
	v_mov_b32_e32 v4, v74
	v_mov_b32_e32 v5, v75
	v_mul_f32_e32 v2, v20, v2
	v_mul_f32_e32 v3, v20, v3
	v_mul_f32_e32 v4, v20, v4
	v_mul_f32_e32 v5, v20, v5
	v_cvt_pk_bf16_f32 v2, v2, v3
	v_cvt_pk_bf16_f32 v3, v4, v5
	global_store_dwordx2 v[8:9], v[2:3], off offset:1024
	s_nop 1
	v_mov_b32_e32 v2, v76
	v_mov_b32_e32 v3, v77
	v_mov_b32_e32 v4, v78
	v_mov_b32_e32 v5, v79
	v_mul_f32_e32 v2, v20, v2
	v_mul_f32_e32 v3, v20, v3
	v_mul_f32_e32 v4, v20, v4
	v_mul_f32_e32 v5, v20, v5
	v_cvt_pk_bf16_f32 v2, v2, v3
	v_cvt_pk_bf16_f32 v3, v4, v5
	global_store_dwordx2 v[8:9], v[2:3], off offset:1536
	s_nop 1
	v_mov_b32_e32 v2, v80
	v_mov_b32_e32 v3, v81
	v_mov_b32_e32 v4, v82
	v_mov_b32_e32 v5, v83
	v_mul_f32_e32 v2, v20, v2
	v_mul_f32_e32 v3, v20, v3
	v_mul_f32_e32 v4, v20, v4
	v_mul_f32_e32 v5, v20, v5
	v_cvt_pk_bf16_f32 v2, v2, v3
	v_cvt_pk_bf16_f32 v3, v4, v5
	global_store_dwordx2 v[8:9], v[2:3], off offset:2048
	s_nop 1
	v_mov_b32_e32 v2, v84
	v_mov_b32_e32 v3, v85
	v_mov_b32_e32 v4, v86
	v_mov_b32_e32 v5, v87
	v_mul_f32_e32 v2, v20, v2
	v_mul_f32_e32 v3, v20, v3
	v_mul_f32_e32 v4, v20, v4
	v_mul_f32_e32 v5, v20, v5
	v_cvt_pk_bf16_f32 v2, v2, v3
	v_cvt_pk_bf16_f32 v3, v4, v5
	global_store_dwordx2 v[8:9], v[2:3], off offset:2560
	s_nop 1
	v_mov_b32_e32 v2, v88
	v_mov_b32_e32 v3, v89
	v_mov_b32_e32 v4, v90
	v_mov_b32_e32 v5, v91
	v_mul_f32_e32 v2, v20, v2
	v_mul_f32_e32 v3, v20, v3
	v_mul_f32_e32 v4, v20, v4
	v_mul_f32_e32 v5, v20, v5
	v_cvt_pk_bf16_f32 v2, v2, v3
	v_cvt_pk_bf16_f32 v3, v4, v5
	global_store_dwordx2 v[8:9], v[2:3], off offset:3072
	s_nop 1
	v_mov_b32_e32 v2, v92
	v_mov_b32_e32 v3, v93
	v_mov_b32_e32 v4, v94
	v_mov_b32_e32 v5, v95
	v_add_co_u32_e32 v10, vcc, s6, v6
	v_mul_f32_e32 v2, v20, v2
	v_mul_f32_e32 v3, v20, v3
	v_addc_co_u32_e32 v11, vcc, 0, v7, vcc
	v_mul_f32_e32 v4, v20, v4
	v_mul_f32_e32 v5, v20, v5
	v_cvt_pk_bf16_f32 v2, v2, v3
	v_cvt_pk_bf16_f32 v3, v4, v5
	global_store_dwordx2 v[8:9], v[2:3], off offset:3584
	s_nop 1
	v_mov_b32_e32 v2, v96
	v_mov_b32_e32 v3, v97
	v_mov_b32_e32 v4, v98
	v_mov_b32_e32 v5, v99
	v_add_co_u32_e32 v16, vcc, s1, v8
	v_lshlrev_b32_e32 v8, 3, v150
	s_nop 0
	v_addc_co_u32_e32 v17, vcc, 0, v9, vcc
	v_add_co_u32_e32 v6, vcc, s7, v6
	v_ashrrev_i32_e32 v9, 31, v8
	s_nop 0
	v_addc_co_u32_e32 v7, vcc, 0, v7, vcc
	v_lshlrev_b64 v[18:19], 1, v[8:9]
	s_mov_b64 s[6:7], 0x4e500100
	s_mov_b64 s[0:1], 0x200
	v_mul_f32_e32 v2, v20, v2
	v_mul_f32_e32 v3, v20, v3
	v_mul_f32_e32 v4, v20, v4
	v_mul_f32_e32 v5, v20, v5
	v_cvt_pk_bf16_f32 v2, v2, v3
	v_cvt_pk_bf16_f32 v3, v4, v5
	global_store_dwordx2 v[16:17], v[2:3], off
	s_nop 1
	v_mov_b32_e32 v2, v100
	v_mov_b32_e32 v3, v101
	v_mov_b32_e32 v4, v102
	v_mov_b32_e32 v5, v103
	v_mul_f32_e32 v2, v20, v2
	v_mul_f32_e32 v3, v20, v3
	v_mul_f32_e32 v4, v20, v4
	v_mul_f32_e32 v5, v20, v5
	v_cvt_pk_bf16_f32 v2, v2, v3
	v_cvt_pk_bf16_f32 v3, v4, v5
	global_store_dwordx2 v[16:17], v[2:3], off offset:512
	s_nop 1
	v_mov_b32_e32 v2, v104
	v_mov_b32_e32 v3, v105
	v_mov_b32_e32 v4, v106
	v_mov_b32_e32 v5, v107
	v_mul_f32_e32 v2, v20, v2
	v_mul_f32_e32 v3, v20, v3
	v_mul_f32_e32 v4, v20, v4
	v_mul_f32_e32 v5, v20, v5
	v_cvt_pk_bf16_f32 v2, v2, v3
	v_cvt_pk_bf16_f32 v3, v4, v5
	global_store_dwordx2 v[16:17], v[2:3], off offset:1024
	s_nop 1
	v_mov_b32_e32 v2, v108
	v_mov_b32_e32 v3, v109
	v_mov_b32_e32 v4, v110
	v_mov_b32_e32 v5, v111
	v_bfi_b32 v10, -16, s4, v134
	v_ashrrev_i32_e32 v11, 31, v10
	v_lshlrev_b64 v[10:11], 13, v[10:11]
	v_or_b32_e32 v10, s10, v10
	v_lshl_add_u64 v[10:11], v[10:11], 0, v[18:19]
	v_lshl_add_u64 v[10:11], s[78:79], 0, v[10:11]
	v_lshl_add_u64 v[10:11], v[10:11], 0, s[8:9]
	v_mul_f32_e32 v2, v20, v2
	v_mul_f32_e32 v3, v20, v3
	v_mul_f32_e32 v4, v20, v4
	v_mul_f32_e32 v5, v20, v5
	v_cvt_pk_bf16_f32 v2, v2, v3
	v_cvt_pk_bf16_f32 v3, v4, v5
	global_store_dwordx2 v[16:17], v[2:3], off offset:1536
	s_nop 1
	v_mov_b32_e32 v2, v112
	v_mov_b32_e32 v3, v113
	v_mov_b32_e32 v4, v114
	v_mov_b32_e32 v5, v115
	v_mul_f32_e32 v2, v20, v2
	v_mul_f32_e32 v3, v20, v3
	v_mul_f32_e32 v4, v20, v4
	v_mul_f32_e32 v5, v20, v5
	v_cvt_pk_bf16_f32 v2, v2, v3
	v_cvt_pk_bf16_f32 v3, v4, v5
	global_store_dwordx2 v[16:17], v[2:3], off offset:2048
	s_nop 1
	v_mov_b32_e32 v2, v116
	v_mov_b32_e32 v3, v117
	v_mov_b32_e32 v4, v118
	v_mov_b32_e32 v5, v119
	v_mul_f32_e32 v2, v20, v2
	v_mul_f32_e32 v3, v20, v3
	v_mul_f32_e32 v4, v20, v4
	v_mul_f32_e32 v5, v20, v5
	v_cvt_pk_bf16_f32 v2, v2, v3
	v_cvt_pk_bf16_f32 v3, v4, v5
	global_store_dwordx2 v[16:17], v[2:3], off offset:2560
	s_nop 1
	v_mov_b32_e32 v2, v120
	v_mov_b32_e32 v3, v121
	v_mov_b32_e32 v4, v122
	v_mov_b32_e32 v5, v123
	v_mul_f32_e32 v2, v20, v2
	v_mul_f32_e32 v3, v20, v3
	v_mul_f32_e32 v4, v20, v4
	v_mul_f32_e32 v5, v20, v5
	v_cvt_pk_bf16_f32 v2, v2, v3
	v_cvt_pk_bf16_f32 v3, v4, v5
	global_store_dwordx2 v[16:17], v[2:3], off offset:3072
	s_nop 1
	v_mov_b32_e32 v12, v124
	v_mov_b32_e32 v13, v125
	v_mov_b32_e32 v14, v126
	v_mov_b32_e32 v15, v127
	v_and_b32_e32 v6, 15, v134
	v_mov_b32_e32 v3, 0
	v_lshl_or_b32 v2, v6, 13, s10
	v_lshl_add_u64 v[8:9], v[2:3], 0, v[18:19]
	v_lshl_add_u64 v[8:9], s[78:79], 0, v[8:9]
	v_mov_b32_e32 v4, v3
	v_mov_b32_e32 v2, v3
	v_lshl_add_u64 v[8:9], v[8:9], 0, s[6:7]
	v_mul_f32_e32 v5, v20, v12
	v_mul_f32_e32 v7, v20, v13
	v_mul_f32_e32 v13, v20, v14
	v_cvt_pk_bf16_f32 v12, v5, v7
	v_mov_b32_e32 v5, v3
	v_mul_f32_e32 v14, v20, v15
	v_cvt_pk_bf16_f32 v13, v13, v14
	global_store_dwordx2 v[16:17], v[12:13], off offset:3584

.LBB0_328:
	s_waitcnt vmcnt(0)
	v_mov_b64_e32 v[6:7], s[92:93]
	flat_load_dwordx2 v[2:3], v[6:7] offset:64 sc0 sc1
	s_waitcnt vmcnt(0)
	s_lshl_b32 s0, s27, 4
	s_lshl_b32 s1, s26, 1
	s_add_i32 s0, s0, s1
	s_ashr_i32 s1, s0, 31
	s_lshl_b64 s[6:7], s[0:1], 2
	s_lshl_b64 s[8:9], s[0:1], 14
	v_lshlrev_b64 v[8:9], 4, v[134:135]
	v_lshl_add_u64 v[12:13], v[134:135], 3, s[14:15]
	s_lshl_b32 s12, s26, 12
	s_and_b32 s12, s12, 0x1000
	s_waitcnt lgkmcnt(0)
	v_lshl_add_u64 v[2:3], v[2:3], 0, s[6:7]
	flat_load_dword v18, v[2:3]
	global_load_dword v128, v[2:3], off offset:4
	s_nop 0
	flat_load_dwordx2 v[2:3], v[6:7] offset:80 sc0 sc1
	s_waitcnt vmcnt(0) lgkmcnt(0)
	v_lshl_add_u64 v[2:3], v[2:3], 0, s[8:9]
	v_lshl_add_u64 v[10:11], v[2:3], 0, v[8:9]
	v_add_co_u32_e32 v212, vcc, 0x1000, v10
	s_nop 1
	v_addc_co_u32_e32 v213, vcc, 0, v11, vcc
	v_add_co_u32_e32 v228, vcc, 0x2000, v10
	s_nop 1
	v_addc_co_u32_e32 v229, vcc, 0, v11, vcc
	v_add_co_u32_e32 v244, vcc, 0x3000, v10
	s_nop 1
	v_addc_co_u32_e32 v245, vcc, 0, v11, vcc
	global_load_dwordx4 v[184:187], v[10:11], off nt
	global_load_dwordx4 v[188:191], v[10:11], off offset:1024 nt
	global_load_dwordx4 v[192:195], v[10:11], off offset:2048 nt
	global_load_dwordx4 v[196:199], v[10:11], off offset:3072 nt
	global_load_dwordx4 v[200:203], v[212:213], off nt
	global_load_dwordx4 v[204:207], v[212:213], off offset:1024 nt
	global_load_dwordx4 v[208:211], v[212:213], off offset:2048 nt
	global_load_dwordx4 v[212:215], v[212:213], off offset:3072 nt
	global_load_dwordx4 v[216:219], v[228:229], off nt
	global_load_dwordx4 v[220:223], v[228:229], off offset:1024 nt
	global_load_dwordx4 v[224:227], v[228:229], off offset:2048 nt
	global_load_dwordx4 v[228:231], v[228:229], off offset:3072 nt
	global_load_dwordx4 v[232:235], v[244:245], off nt
	global_load_dwordx4 v[236:239], v[244:245], off offset:1024 nt
	global_load_dwordx4 v[240:243], v[244:245], off offset:2048 nt
	global_load_dwordx4 v[244:247], v[244:245], off offset:3072 nt
	v_add_co_u32_e32 v76, vcc, 0x4000, v10
	s_nop 1
	v_addc_co_u32_e32 v77, vcc, 0, v11, vcc
	v_add_co_u32_e32 v92, vcc, 0x5000, v10
	s_nop 1
	v_addc_co_u32_e32 v93, vcc, 0, v11, vcc
	v_add_co_u32_e32 v108, vcc, 0x6000, v10
	s_nop 1
	v_addc_co_u32_e32 v109, vcc, 0, v11, vcc
	v_add_co_u32_e32 v124, vcc, 0x7000, v10
	s_nop 1
	v_addc_co_u32_e32 v125, vcc, 0, v11, vcc
	global_load_dwordx4 v[64:67], v[76:77], off nt
	global_load_dwordx4 v[68:71], v[76:77], off offset:1024 nt
	global_load_dwordx4 v[72:75], v[76:77], off offset:2048 nt
	global_load_dwordx4 v[76:79], v[76:77], off offset:3072 nt
	global_load_dwordx4 v[80:83], v[92:93], off nt
	global_load_dwordx4 v[84:87], v[92:93], off offset:1024 nt
	global_load_dwordx4 v[88:91], v[92:93], off offset:2048 nt
	global_load_dwordx4 v[92:95], v[92:93], off offset:3072 nt
	global_load_dwordx4 v[96:99], v[108:109], off nt
	global_load_dwordx4 v[100:103], v[108:109], off offset:1024 nt
	global_load_dwordx4 v[104:107], v[108:109], off offset:2048 nt
	global_load_dwordx4 v[108:111], v[108:109], off offset:3072 nt
	global_load_dwordx4 v[112:115], v[124:125], off nt
	global_load_dwordx4 v[116:119], v[124:125], off offset:1024 nt
	global_load_dwordx4 v[120:123], v[124:125], off offset:2048 nt
	global_load_dwordx4 v[124:127], v[124:125], off offset:3072 nt
	s_lshl_b64 s[8:9], s[0:1], 13
	v_lshl_add_u64 v[14:15], v[12:13], 0, s[8:9]
	s_movk_i32 s1, 0x1000
	v_add_co_u32_e32 v16, vcc, s1, v10
	s_movk_i32 s8, 0x2000
	s_nop 0
	v_addc_co_u32_e32 v17, vcc, 0, v11, vcc
	s_movk_i32 s9, 0x3000
	s_waitcnt vmcnt(0) lgkmcnt(0)
	v_mov_b32_e32 v2, v184
	v_mov_b32_e32 v3, v185
	v_mov_b32_e32 v4, v186
	v_mov_b32_e32 v5, v187
	v_mul_f32_e32 v2, v18, v2
	v_mul_f32_e32 v3, v18, v3
	v_mul_f32_e32 v4, v18, v4
	v_mul_f32_e32 v5, v18, v5
	v_cvt_pk_bf16_f32 v2, v2, v3
	v_cvt_pk_bf16_f32 v3, v4, v5
	global_store_dwordx2 v[14:15], v[2:3], off
	s_nop 1
	v_mov_b32_e32 v2, v188
	v_mov_b32_e32 v3, v189
	v_mov_b32_e32 v4, v190
	v_mov_b32_e32 v5, v191
	v_mul_f32_e32 v2, v18, v2
	v_mul_f32_e32 v3, v18, v3
	v_mul_f32_e32 v4, v18, v4
	v_mul_f32_e32 v5, v18, v5
	v_cvt_pk_bf16_f32 v2, v2, v3
	v_cvt_pk_bf16_f32 v3, v4, v5
	global_store_dwordx2 v[14:15], v[2:3], off offset:512
	s_nop 1
	v_mov_b32_e32 v2, v192
	v_mov_b32_e32 v3, v193
	v_mov_b32_e32 v4, v194
	v_mov_b32_e32 v5, v195
	v_mul_f32_e32 v2, v18, v2
	v_mul_f32_e32 v3, v18, v3
	v_mul_f32_e32 v4, v18, v4
	v_mul_f32_e32 v5, v18, v5
	v_cvt_pk_bf16_f32 v2, v2, v3
	v_cvt_pk_bf16_f32 v3, v4, v5
	global_store_dwordx2 v[14:15], v[2:3], off offset:1024
	s_nop 1
	v_mov_b32_e32 v2, v196
	v_mov_b32_e32 v3, v197
	v_mov_b32_e32 v4, v198
	v_mov_b32_e32 v5, v199
	v_mul_f32_e32 v2, v18, v2
	v_mul_f32_e32 v3, v18, v3
	v_mul_f32_e32 v4, v18, v4
	v_mul_f32_e32 v5, v18, v5
	v_cvt_pk_bf16_f32 v2, v2, v3
	v_cvt_pk_bf16_f32 v3, v4, v5
	global_store_dwordx2 v[14:15], v[2:3], off offset:1536
	s_nop 1
	v_mov_b32_e32 v2, v200
	v_mov_b32_e32 v3, v201
	v_mov_b32_e32 v4, v202
	v_mov_b32_e32 v5, v203
	v_mul_f32_e32 v2, v18, v2
	v_mul_f32_e32 v3, v18, v3
	v_mul_f32_e32 v4, v18, v4
	v_mul_f32_e32 v5, v18, v5
	v_cvt_pk_bf16_f32 v2, v2, v3
	v_cvt_pk_bf16_f32 v3, v4, v5
	global_store_dwordx2 v[14:15], v[2:3], off offset:2048
	s_nop 1
	v_mov_b32_e32 v2, v204
	v_mov_b32_e32 v3, v205
	v_mov_b32_e32 v4, v206
	v_mov_b32_e32 v5, v207
	v_mul_f32_e32 v2, v18, v2
	v_mul_f32_e32 v3, v18, v3
	v_mul_f32_e32 v4, v18, v4
	v_mul_f32_e32 v5, v18, v5
	v_cvt_pk_bf16_f32 v2, v2, v3
	v_cvt_pk_bf16_f32 v3, v4, v5
	global_store_dwordx2 v[14:15], v[2:3], off offset:2560
	s_nop 1
	v_mov_b32_e32 v2, v208
	v_mov_b32_e32 v3, v209
	v_mov_b32_e32 v4, v210
	v_mov_b32_e32 v5, v211
	v_mul_f32_e32 v2, v18, v2
	v_mul_f32_e32 v3, v18, v3
	v_mul_f32_e32 v4, v18, v4
	v_mul_f32_e32 v5, v18, v5
	v_cvt_pk_bf16_f32 v2, v2, v3
	v_cvt_pk_bf16_f32 v3, v4, v5
	global_store_dwordx2 v[14:15], v[2:3], off offset:3072
	s_nop 1
	v_mov_b32_e32 v2, v212
	v_mov_b32_e32 v3, v213
	v_mov_b32_e32 v4, v214
	v_mov_b32_e32 v5, v215
	v_add_co_u32_e32 v16, vcc, s8, v10
	v_mul_f32_e32 v2, v18, v2
	v_mul_f32_e32 v3, v18, v3
	v_addc_co_u32_e32 v17, vcc, 0, v11, vcc
	v_mul_f32_e32 v4, v18, v4
	v_mul_f32_e32 v5, v18, v5
	v_cvt_pk_bf16_f32 v2, v2, v3
	v_cvt_pk_bf16_f32 v3, v4, v5
	global_store_dwordx2 v[14:15], v[2:3], off offset:3584
	s_nop 1
	v_mov_b32_e32 v2, v216
	v_mov_b32_e32 v3, v217
	v_mov_b32_e32 v4, v218
	v_mov_b32_e32 v5, v219
	v_add_co_u32_e32 v14, vcc, s1, v14
	v_mul_f32_e32 v2, v18, v2
	v_addc_co_u32_e32 v15, vcc, 0, v15, vcc
	v_mul_f32_e32 v3, v18, v3
	v_mul_f32_e32 v4, v18, v4
	v_mul_f32_e32 v5, v18, v5
	v_cvt_pk_bf16_f32 v2, v2, v3
	v_cvt_pk_bf16_f32 v3, v4, v5
	global_store_dwordx2 v[14:15], v[2:3], off
	s_nop 1
	v_mov_b32_e32 v2, v220
	v_mov_b32_e32 v3, v221
	v_mov_b32_e32 v4, v222
	v_mov_b32_e32 v5, v223
	v_add_co_u32_e32 v10, vcc, s9, v10
	v_mul_f32_e32 v2, v18, v2
	v_mul_f32_e32 v3, v18, v3
	v_mul_f32_e32 v4, v18, v4
	v_mul_f32_e32 v5, v18, v5
	v_cvt_pk_bf16_f32 v2, v2, v3
	v_cvt_pk_bf16_f32 v3, v4, v5
	global_store_dwordx2 v[14:15], v[2:3], off offset:512
	s_nop 1
	v_mov_b32_e32 v2, v224
	v_mov_b32_e32 v3, v225
	v_mov_b32_e32 v4, v226
	v_mov_b32_e32 v5, v227
	v_addc_co_u32_e32 v11, vcc, 0, v11, vcc
	v_mul_f32_e32 v2, v18, v2
	v_mul_f32_e32 v3, v18, v3
	v_mul_f32_e32 v4, v18, v4
	v_mul_f32_e32 v5, v18, v5
	v_cvt_pk_bf16_f32 v2, v2, v3
	v_cvt_pk_bf16_f32 v3, v4, v5
	global_store_dwordx2 v[14:15], v[2:3], off offset:1024
	s_nop 1
	v_mov_b32_e32 v2, v228
	v_mov_b32_e32 v3, v229
	v_mov_b32_e32 v4, v230
	v_mov_b32_e32 v5, v231
	v_mul_f32_e32 v2, v18, v2
	v_mul_f32_e32 v3, v18, v3
	v_mul_f32_e32 v4, v18, v4
	v_mul_f32_e32 v5, v18, v5
	v_cvt_pk_bf16_f32 v2, v2, v3
	v_cvt_pk_bf16_f32 v3, v4, v5
	global_store_dwordx2 v[14:15], v[2:3], off offset:1536
	s_nop 1
	v_mov_b32_e32 v2, v232
	v_mov_b32_e32 v3, v233
	v_mov_b32_e32 v4, v234
	v_mov_b32_e32 v5, v235
	v_mul_f32_e32 v2, v18, v2
	v_mul_f32_e32 v3, v18, v3
	v_mul_f32_e32 v4, v18, v4
	v_mul_f32_e32 v5, v18, v5
	v_cvt_pk_bf16_f32 v2, v2, v3
	v_cvt_pk_bf16_f32 v3, v4, v5
	global_store_dwordx2 v[14:15], v[2:3], off offset:2048
	s_nop 1
	v_mov_b32_e32 v2, v236
	v_mov_b32_e32 v3, v237
	v_mov_b32_e32 v4, v238
	v_mov_b32_e32 v5, v239
	v_mul_f32_e32 v2, v18, v2
	v_mul_f32_e32 v3, v18, v3
	v_mul_f32_e32 v4, v18, v4
	v_mul_f32_e32 v5, v18, v5
	v_cvt_pk_bf16_f32 v2, v2, v3
	v_cvt_pk_bf16_f32 v3, v4, v5
	global_store_dwordx2 v[14:15], v[2:3], off offset:2560
	s_nop 1
	v_mov_b32_e32 v2, v240
	v_mov_b32_e32 v3, v241
	v_mov_b32_e32 v4, v242
	v_mov_b32_e32 v5, v243
	v_mul_f32_e32 v2, v18, v2
	v_mul_f32_e32 v3, v18, v3
	v_mul_f32_e32 v4, v18, v4
	v_mul_f32_e32 v5, v18, v5
	v_cvt_pk_bf16_f32 v2, v2, v3
	v_cvt_pk_bf16_f32 v3, v4, v5
	global_store_dwordx2 v[14:15], v[2:3], off offset:3072
	s_nop 1
	v_mov_b32_e32 v2, v244
	v_mov_b32_e32 v3, v245
	v_mov_b32_e32 v4, v246
	v_mov_b32_e32 v5, v247
	v_mul_f32_e32 v2, v18, v2
	v_mul_f32_e32 v3, v18, v3
	v_mul_f32_e32 v4, v18, v4
	v_mul_f32_e32 v5, v18, v5
	v_cvt_pk_bf16_f32 v2, v2, v3
	v_cvt_pk_bf16_f32 v3, v4, v5
	global_store_dwordx2 v[14:15], v[2:3], off offset:3584
	v_lshl_add_u64 v[2:3], v[2:3], 0, s[6:7]
	s_nop 0
	s_or_b32 s6, s0, 1
	s_ashr_i32 s7, s6, 31
	s_lshl_b64 s[10:11], s[6:7], 14
	s_lshl_b64 s[6:7], s[6:7], 13
	s_waitcnt lgkmcnt(0)
	v_lshl_add_u64 v[2:3], v[2:3], 0, s[10:11]
	v_lshl_add_u64 v[6:7], v[2:3], 0, v[8:9]
	v_lshl_add_u64 v[8:9], v[12:13], 0, s[6:7]
	v_add_co_u32_e32 v10, vcc, s1, v6
	s_add_i32 s6, s26, s57
	s_nop 0
	v_addc_co_u32_e32 v11, vcc, 0, v7, vcc
	s_lshl_b32 s6, s6, 3
	s_mov_b64 s[10:11], 0x26000100
	s_movk_i32 s7, 0xffe0
	s_waitcnt vmcnt(16) lgkmcnt(0)
	v_mov_b32_e32 v20, v128
	v_mov_b32_e32 v2, v64
	v_mov_b32_e32 v3, v65
	v_mov_b32_e32 v4, v66
	v_mov_b32_e32 v5, v67
	v_mul_f32_e32 v2, v20, v2
	v_mul_f32_e32 v3, v20, v3
	v_mul_f32_e32 v4, v20, v4
	v_mul_f32_e32 v5, v20, v5
	v_cvt_pk_bf16_f32 v2, v2, v3
	v_cvt_pk_bf16_f32 v3, v4, v5
	global_store_dwordx2 v[8:9], v[2:3], off
	s_nop 1
	v_mov_b32_e32 v2, v68
	v_mov_b32_e32 v3, v69
	v_mov_b32_e32 v4, v70
	v_mov_b32_e32 v5, v71
	v_mul_f32_e32 v2, v20, v2
	v_mul_f32_e32 v3, v20, v3
	v_mul_f32_e32 v4, v20, v4
	v_mul_f32_e32 v5, v20, v5
	v_cvt_pk_bf16_f32 v2, v2, v3
	v_cvt_pk_bf16_f32 v3, v4, v5
	global_store_dwordx2 v[8:9], v[2:3], off offset:512
	s_nop 1
	v_mov_b32_e32 v2, v72
	v_mov_b32_e32 v3, v73
	v_mov_b32_e32 v4, v74
	v_mov_b32_e32 v5, v75
	v_mul_f32_e32 v2, v20, v2
	v_mul_f32_e32 v3, v20, v3
	v_mul_f32_e32 v4, v20, v4
	v_mul_f32_e32 v5, v20, v5
	v_cvt_pk_bf16_f32 v2, v2, v3
	v_cvt_pk_bf16_f32 v3, v4, v5
	global_store_dwordx2 v[8:9], v[2:3], off offset:1024
	s_nop 1
	v_mov_b32_e32 v2, v76
	v_mov_b32_e32 v3, v77
	v_mov_b32_e32 v4, v78
	v_mov_b32_e32 v5, v79
	v_mul_f32_e32 v2, v20, v2
	v_mul_f32_e32 v3, v20, v3
	v_mul_f32_e32 v4, v20, v4
	v_mul_f32_e32 v5, v20, v5
	v_cvt_pk_bf16_f32 v2, v2, v3
	v_cvt_pk_bf16_f32 v3, v4, v5
	global_store_dwordx2 v[8:9], v[2:3], off offset:1536
	s_nop 1
	v_mov_b32_e32 v2, v80
	v_mov_b32_e32 v3, v81
	v_mov_b32_e32 v4, v82
	v_mov_b32_e32 v5, v83
	v_mul_f32_e32 v2, v20, v2
	v_mul_f32_e32 v3, v20, v3
	v_mul_f32_e32 v4, v20, v4
	v_mul_f32_e32 v5, v20, v5
	v_cvt_pk_bf16_f32 v2, v2, v3
	v_cvt_pk_bf16_f32 v3, v4, v5
	global_store_dwordx2 v[8:9], v[2:3], off offset:2048
	s_nop 1
	v_mov_b32_e32 v2, v84
	v_mov_b32_e32 v3, v85
	v_mov_b32_e32 v4, v86
	v_mov_b32_e32 v5, v87
	v_mul_f32_e32 v2, v20, v2
	v_mul_f32_e32 v3, v20, v3
	v_mul_f32_e32 v4, v20, v4
	v_mul_f32_e32 v5, v20, v5
	v_cvt_pk_bf16_f32 v2, v2, v3
	v_cvt_pk_bf16_f32 v3, v4, v5
	global_store_dwordx2 v[8:9], v[2:3], off offset:2560
	s_nop 1
	v_mov_b32_e32 v2, v88
	v_mov_b32_e32 v3, v89
	v_mov_b32_e32 v4, v90
	v_mov_b32_e32 v5, v91
	v_mul_f32_e32 v2, v20, v2
	v_mul_f32_e32 v3, v20, v3
	v_mul_f32_e32 v4, v20, v4
	v_mul_f32_e32 v5, v20, v5
	v_cvt_pk_bf16_f32 v2, v2, v3
	v_cvt_pk_bf16_f32 v3, v4, v5
	global_store_dwordx2 v[8:9], v[2:3], off offset:3072
	s_nop 1
	v_mov_b32_e32 v2, v92
	v_mov_b32_e32 v3, v93
	v_mov_b32_e32 v4, v94
	v_mov_b32_e32 v5, v95
	v_add_co_u32_e32 v10, vcc, s8, v6
	v_mul_f32_e32 v2, v20, v2
	v_mul_f32_e32 v3, v20, v3
	v_addc_co_u32_e32 v11, vcc, 0, v7, vcc
	v_mul_f32_e32 v4, v20, v4
	v_mul_f32_e32 v5, v20, v5
	v_cvt_pk_bf16_f32 v2, v2, v3
	v_cvt_pk_bf16_f32 v3, v4, v5
	global_store_dwordx2 v[8:9], v[2:3], off offset:3584
	s_nop 1
	v_mov_b32_e32 v2, v96
	v_mov_b32_e32 v3, v97
	v_mov_b32_e32 v4, v98
	v_mov_b32_e32 v5, v99
	v_add_co_u32_e32 v16, vcc, s1, v8
	v_lshlrev_b32_e32 v8, 3, v150
	s_nop 0
	v_addc_co_u32_e32 v17, vcc, 0, v9, vcc
	v_add_co_u32_e32 v6, vcc, s9, v6
	v_ashrrev_i32_e32 v9, 31, v8
	s_nop 0
	v_addc_co_u32_e32 v7, vcc, 0, v7, vcc
	v_lshlrev_b64 v[18:19], 1, v[8:9]
	s_mov_b64 s[8:9], 0x4e500100
	s_mov_b64 s[0:1], 0x200
	v_mul_f32_e32 v2, v20, v2
	v_mul_f32_e32 v3, v20, v3
	v_mul_f32_e32 v4, v20, v4
	v_mul_f32_e32 v5, v20, v5
	v_cvt_pk_bf16_f32 v2, v2, v3
	v_cvt_pk_bf16_f32 v3, v4, v5
	global_store_dwordx2 v[16:17], v[2:3], off
	s_nop 1
	v_mov_b32_e32 v2, v100
	v_mov_b32_e32 v3, v101
	v_mov_b32_e32 v4, v102
	v_mov_b32_e32 v5, v103
	v_mul_f32_e32 v2, v20, v2
	v_mul_f32_e32 v3, v20, v3
	v_mul_f32_e32 v4, v20, v4
	v_mul_f32_e32 v5, v20, v5
	v_cvt_pk_bf16_f32 v2, v2, v3
	v_cvt_pk_bf16_f32 v3, v4, v5
	global_store_dwordx2 v[16:17], v[2:3], off offset:512
	s_nop 1
	v_mov_b32_e32 v2, v104
	v_mov_b32_e32 v3, v105
	v_mov_b32_e32 v4, v106
	v_mov_b32_e32 v5, v107
	v_mul_f32_e32 v2, v20, v2
	v_mul_f32_e32 v3, v20, v3
	v_mul_f32_e32 v4, v20, v4
	v_mul_f32_e32 v5, v20, v5
	v_cvt_pk_bf16_f32 v2, v2, v3
	v_cvt_pk_bf16_f32 v3, v4, v5
	global_store_dwordx2 v[16:17], v[2:3], off offset:1024
	s_nop 1
	v_mov_b32_e32 v2, v108
	v_mov_b32_e32 v3, v109
	v_mov_b32_e32 v4, v110
	v_mov_b32_e32 v5, v111
	v_bfi_b32 v10, -16, s6, v134
	v_ashrrev_i32_e32 v11, 31, v10
	v_lshlrev_b64 v[10:11], 13, v[10:11]
	v_or_b32_e32 v10, s12, v10
	v_lshl_add_u64 v[10:11], v[10:11], 0, v[18:19]
	v_lshl_add_u64 v[10:11], s[78:79], 0, v[10:11]
	v_lshl_add_u64 v[10:11], v[10:11], 0, s[10:11]
	v_mul_f32_e32 v2, v20, v2
	v_mul_f32_e32 v3, v20, v3
	v_mul_f32_e32 v4, v20, v4
	v_mul_f32_e32 v5, v20, v5
	v_cvt_pk_bf16_f32 v2, v2, v3
	v_cvt_pk_bf16_f32 v3, v4, v5
	global_store_dwordx2 v[16:17], v[2:3], off offset:1536
	s_nop 1
	v_mov_b32_e32 v2, v112
	v_mov_b32_e32 v3, v113
	v_mov_b32_e32 v4, v114
	v_mov_b32_e32 v5, v115
	v_mul_f32_e32 v2, v20, v2
	v_mul_f32_e32 v3, v20, v3
	v_mul_f32_e32 v4, v20, v4
	v_mul_f32_e32 v5, v20, v5
	v_cvt_pk_bf16_f32 v2, v2, v3
	v_cvt_pk_bf16_f32 v3, v4, v5
	global_store_dwordx2 v[16:17], v[2:3], off offset:2048
	s_nop 1
	v_mov_b32_e32 v2, v116
	v_mov_b32_e32 v3, v117
	v_mov_b32_e32 v4, v118
	v_mov_b32_e32 v5, v119
	v_mul_f32_e32 v2, v20, v2
	v_mul_f32_e32 v3, v20, v3
	v_mul_f32_e32 v4, v20, v4
	v_mul_f32_e32 v5, v20, v5
	v_cvt_pk_bf16_f32 v2, v2, v3
	v_cvt_pk_bf16_f32 v3, v4, v5
	global_store_dwordx2 v[16:17], v[2:3], off offset:2560
	s_nop 1
	v_mov_b32_e32 v2, v120
	v_mov_b32_e32 v3, v121
	v_mov_b32_e32 v4, v122
	v_mov_b32_e32 v5, v123
	v_mul_f32_e32 v2, v20, v2
	v_mul_f32_e32 v3, v20, v3
	v_mul_f32_e32 v4, v20, v4
	v_mul_f32_e32 v5, v20, v5
	v_cvt_pk_bf16_f32 v2, v2, v3
	v_cvt_pk_bf16_f32 v3, v4, v5
	global_store_dwordx2 v[16:17], v[2:3], off offset:3072
	s_nop 1
	v_mov_b32_e32 v12, v124
	v_mov_b32_e32 v13, v125
	v_mov_b32_e32 v14, v126
	v_mov_b32_e32 v15, v127
	v_and_b32_e32 v6, 15, v134
	v_mov_b32_e32 v3, 0
	v_lshl_or_b32 v2, v6, 13, s12
	v_lshl_add_u64 v[8:9], v[2:3], 0, v[18:19]
	v_lshl_add_u64 v[8:9], s[78:79], 0, v[8:9]
	v_mov_b32_e32 v4, v3
	v_mov_b32_e32 v2, v3
	v_lshl_add_u64 v[8:9], v[8:9], 0, s[8:9]
	v_mul_f32_e32 v5, v20, v12
	v_mul_f32_e32 v7, v20, v13
	v_mul_f32_e32 v13, v20, v14
	v_cvt_pk_bf16_f32 v12, v5, v7
	v_mov_b32_e32 v5, v3
	v_mul_f32_e32 v14, v20, v15
	v_cvt_pk_bf16_f32 v13, v13, v14
	global_store_dwordx2 v[16:17], v[12:13], off offset:3584
